# P8: final RMSNorm fused into the down-GEMM tile epilogue (x2 kept f32 in accumulators, per-row sums of squares exchanged through scratch + panel counter; no bf16 x2 round trip, no second pass)
# speedup vs baseline: 1.0230x; 1.0230x over previous
.LBB0_991:
	s_and_b64 vcc, exec, s[36:37]
	s_cbranch_vccnz .Lfz_epi
	s_lshl_b32 s8, s22, 8
	v_add_u32_e32 v180, s8, v165
	v_lshl_or_b32 v160, s58, 8, v169
	v_readlane_b32 s4, v249, 44
	v_readlane_b32 s5, v249, 45
	s_ashr_i32 s0, s22, 3
	s_mul_hi_i32 s1, s0, 0x6000
	s_mulk_i32 s0, 0x6000
	s_add_u32 s0, s64, s0
	s_addc_u32 s1, s65, s1
	v_mov_b32_e32 v161, 0
	v_lshl_add_u32 v158, v180, 10, v160
	v_mov_b32_e32 v159, 0
	v_lshl_add_u64 v[156:157], v[160:161], 2, s[0:1]
	v_lshl_add_u64 v[162:163], v[158:159], 1, s[4:5]
	v_lshlrev_b32_e32 v181, 1, v158
	global_load_dwordx4 v[132:135], v[156:157], off
	global_load_dwordx4 v[128:131], v[156:157], off offset:16
	s_mov_b32 s10, 0x8000
	s_mov_b32 s11, 0
	s_mov_b32 s12, 0x28000
	s_mov_b32 s13, 0
	s_mov_b32 s14, 0x8000
	s_mov_b32 s15, 0x10000
	s_mov_b32 s23, 0x18000
	s_mov_b32 s24, 0x40000
	s_mov_b32 s32, 0x48000
	s_mov_b32 s55, 0x50000
	s_mov_b32 s74, 0x58000
	v_mov_b64_e32 v[192:193], v[162:163]
	global_load_dwordx4 v[200:203], v[192:193], off nt
	v_lshl_add_u64 v[192:193], v[192:193], 0, s[10:11]
	global_load_dwordx4 v[204:207], v[192:193], off nt
	global_load_dwordx4 v[184:187], v[156:157], off offset:512
	global_load_dwordx4 v[188:191], v[156:157], off offset:528
	v_lshl_add_u64 v[192:193], v[192:193], 0, s[10:11]
	global_load_dwordx4 v[208:211], v[192:193], off nt
	v_lshl_add_u64 v[192:193], v[192:193], 0, s[10:11]
	global_load_dwordx4 v[212:215], v[192:193], off nt
	v_lshl_add_u64 v[192:193], v[192:193], 0, s[12:13]
	global_load_dwordx4 v[216:219], v[192:193], off nt
	v_lshl_add_u64 v[192:193], v[192:193], 0, s[10:11]
	global_load_dwordx4 v[220:223], v[192:193], off nt
	s_waitcnt vmcnt(7)
	v_lshlrev_b32_e32 v224, 16, v200
	v_and_b32_e32 v225, 0xffff0000, v200
	v_lshlrev_b32_e32 v226, 16, v201
	v_and_b32_e32 v227, 0xffff0000, v201
	v_lshlrev_b32_e32 v228, 16, v202
	v_and_b32_e32 v229, 0xffff0000, v202
	v_lshlrev_b32_e32 v230, 16, v203
	v_and_b32_e32 v231, 0xffff0000, v203
	v_pk_fma_f32 v[124:125], v[124:125], v[132:133], v[224:225]
	v_pk_fma_f32 v[126:127], v[126:127], v[134:135], v[226:227]
	v_pk_fma_f32 v[120:121], v[120:121], v[128:129], v[228:229]
	v_pk_fma_f32 v[122:123], v[122:123], v[130:131], v[230:231]
	v_cvt_pk_bf16_f32 v200, v124, v125
	v_cvt_pk_bf16_f32 v201, v126, v127
	v_cvt_pk_bf16_f32 v202, v120, v121
	v_cvt_pk_bf16_f32 v203, v122, v123
	buffer_store_dwordx4 v[200:203], v181, s[16:19], 0 offen sc1
	s_nop 0
	v_lshl_add_u64 v[192:193], v[192:193], 0, s[10:11]
	global_load_dwordx4 v[200:203], v[192:193], off nt
	s_waitcnt vmcnt(8)
	v_lshlrev_b32_e32 v224, 16, v204
	v_and_b32_e32 v225, 0xffff0000, v204
	v_lshlrev_b32_e32 v226, 16, v205
	v_and_b32_e32 v227, 0xffff0000, v205
	v_lshlrev_b32_e32 v228, 16, v206
	v_and_b32_e32 v229, 0xffff0000, v206
	v_lshlrev_b32_e32 v230, 16, v207
	v_and_b32_e32 v231, 0xffff0000, v207
	v_pk_fma_f32 v[116:117], v[116:117], v[132:133], v[224:225]
	v_pk_fma_f32 v[118:119], v[118:119], v[134:135], v[226:227]
	v_pk_fma_f32 v[112:113], v[112:113], v[128:129], v[228:229]
	v_pk_fma_f32 v[114:115], v[114:115], v[130:131], v[230:231]
	v_cvt_pk_bf16_f32 v204, v116, v117
	v_cvt_pk_bf16_f32 v205, v118, v119
	v_cvt_pk_bf16_f32 v206, v112, v113
	v_cvt_pk_bf16_f32 v207, v114, v115
	buffer_store_dwordx4 v[204:207], v181, s[16:19], s14 offen sc1
	s_nop 0
	v_lshl_add_u64 v[192:193], v[192:193], 0, s[10:11]
	global_load_dwordx4 v[204:207], v[192:193], off nt
	s_waitcnt vmcnt(7)
	v_lshlrev_b32_e32 v224, 16, v208
	v_and_b32_e32 v225, 0xffff0000, v208
	v_lshlrev_b32_e32 v226, 16, v209
	v_and_b32_e32 v227, 0xffff0000, v209
	v_lshlrev_b32_e32 v228, 16, v210
	v_and_b32_e32 v229, 0xffff0000, v210
	v_lshlrev_b32_e32 v230, 16, v211
	v_and_b32_e32 v231, 0xffff0000, v211
	v_pk_fma_f32 v[108:109], v[108:109], v[132:133], v[224:225]
	v_pk_fma_f32 v[110:111], v[110:111], v[134:135], v[226:227]
	v_pk_fma_f32 v[104:105], v[104:105], v[128:129], v[228:229]
	v_pk_fma_f32 v[106:107], v[106:107], v[130:131], v[230:231]
	v_cvt_pk_bf16_f32 v208, v108, v109
	v_cvt_pk_bf16_f32 v209, v110, v111
	v_cvt_pk_bf16_f32 v210, v104, v105
	v_cvt_pk_bf16_f32 v211, v106, v107
	buffer_store_dwordx4 v[208:211], v181, s[16:19], s15 offen sc1
	s_nop 0
	v_mov_b64_e32 v[192:193], v[162:163]
	global_load_dwordx4 v[208:211], v[192:193], off offset:256 nt
	s_waitcnt vmcnt(8)
	v_lshlrev_b32_e32 v224, 16, v212
	v_and_b32_e32 v225, 0xffff0000, v212
	v_lshlrev_b32_e32 v226, 16, v213
	v_and_b32_e32 v227, 0xffff0000, v213
	v_lshlrev_b32_e32 v228, 16, v214
	v_and_b32_e32 v229, 0xffff0000, v214
	v_lshlrev_b32_e32 v230, 16, v215
	v_and_b32_e32 v231, 0xffff0000, v215
	v_pk_fma_f32 v[100:101], v[100:101], v[132:133], v[224:225]
	v_pk_fma_f32 v[102:103], v[102:103], v[134:135], v[226:227]
	v_pk_fma_f32 v[96:97], v[96:97], v[128:129], v[228:229]
	v_pk_fma_f32 v[98:99], v[98:99], v[130:131], v[230:231]
	v_cvt_pk_bf16_f32 v212, v100, v101
	v_cvt_pk_bf16_f32 v213, v102, v103
	v_cvt_pk_bf16_f32 v214, v96, v97
	v_cvt_pk_bf16_f32 v215, v98, v99
	buffer_store_dwordx4 v[212:215], v181, s[16:19], s23 offen sc1
	s_nop 0
	v_lshl_add_u64 v[192:193], v[192:193], 0, s[10:11]
	global_load_dwordx4 v[212:215], v[192:193], off offset:256 nt
	s_waitcnt vmcnt(9)
	v_lshlrev_b32_e32 v224, 16, v216
	v_and_b32_e32 v225, 0xffff0000, v216
	v_lshlrev_b32_e32 v226, 16, v217
	v_and_b32_e32 v227, 0xffff0000, v217
	v_lshlrev_b32_e32 v228, 16, v218
	v_and_b32_e32 v229, 0xffff0000, v218
	v_lshlrev_b32_e32 v230, 16, v219
	v_and_b32_e32 v231, 0xffff0000, v219
	v_pk_fma_f32 v[92:93], v[92:93], v[132:133], v[224:225]
	v_pk_fma_f32 v[94:95], v[94:95], v[134:135], v[226:227]
	v_pk_fma_f32 v[88:89], v[88:89], v[128:129], v[228:229]
	v_pk_fma_f32 v[90:91], v[90:91], v[130:131], v[230:231]
	v_cvt_pk_bf16_f32 v216, v92, v93
	v_cvt_pk_bf16_f32 v217, v94, v95
	v_cvt_pk_bf16_f32 v218, v88, v89
	v_cvt_pk_bf16_f32 v219, v90, v91
	buffer_store_dwordx4 v[216:219], v181, s[16:19], s24 offen sc1
	s_nop 0
	v_lshl_add_u64 v[192:193], v[192:193], 0, s[10:11]
	global_load_dwordx4 v[216:219], v[192:193], off offset:256 nt
	s_waitcnt vmcnt(10)
	v_lshlrev_b32_e32 v224, 16, v220
	v_and_b32_e32 v225, 0xffff0000, v220
	v_lshlrev_b32_e32 v226, 16, v221
	v_and_b32_e32 v227, 0xffff0000, v221
	v_lshlrev_b32_e32 v228, 16, v222
	v_and_b32_e32 v229, 0xffff0000, v222
	v_lshlrev_b32_e32 v230, 16, v223
	v_and_b32_e32 v231, 0xffff0000, v223
	v_pk_fma_f32 v[84:85], v[84:85], v[132:133], v[224:225]
	v_pk_fma_f32 v[86:87], v[86:87], v[134:135], v[226:227]
	v_pk_fma_f32 v[80:81], v[80:81], v[128:129], v[228:229]
	v_pk_fma_f32 v[82:83], v[82:83], v[130:131], v[230:231]
	v_cvt_pk_bf16_f32 v220, v84, v85
	v_cvt_pk_bf16_f32 v221, v86, v87
	v_cvt_pk_bf16_f32 v222, v80, v81
	v_cvt_pk_bf16_f32 v223, v82, v83
	buffer_store_dwordx4 v[220:223], v181, s[16:19], s32 offen sc1
	s_nop 0
	v_lshl_add_u64 v[192:193], v[192:193], 0, s[10:11]
	global_load_dwordx4 v[220:223], v[192:193], off offset:256 nt
	s_waitcnt vmcnt(10)
	v_lshlrev_b32_e32 v224, 16, v200
	v_and_b32_e32 v225, 0xffff0000, v200
	v_lshlrev_b32_e32 v226, 16, v201
	v_and_b32_e32 v227, 0xffff0000, v201
	v_lshlrev_b32_e32 v228, 16, v202
	v_and_b32_e32 v229, 0xffff0000, v202
	v_lshlrev_b32_e32 v230, 16, v203
	v_and_b32_e32 v231, 0xffff0000, v203
	v_pk_fma_f32 v[76:77], v[76:77], v[132:133], v[224:225]
	v_pk_fma_f32 v[78:79], v[78:79], v[134:135], v[226:227]
	v_pk_fma_f32 v[72:73], v[72:73], v[128:129], v[228:229]
	v_pk_fma_f32 v[74:75], v[74:75], v[130:131], v[230:231]
	v_cvt_pk_bf16_f32 v200, v76, v77
	v_cvt_pk_bf16_f32 v201, v78, v79
	v_cvt_pk_bf16_f32 v202, v72, v73
	v_cvt_pk_bf16_f32 v203, v74, v75
	buffer_store_dwordx4 v[200:203], v181, s[16:19], s55 offen sc1
	s_nop 0
	v_lshl_add_u64 v[192:193], v[192:193], 0, s[12:13]
	global_load_dwordx4 v[200:203], v[192:193], off offset:256 nt
	s_waitcnt vmcnt(10)
	v_lshlrev_b32_e32 v224, 16, v204
	v_and_b32_e32 v225, 0xffff0000, v204
	v_lshlrev_b32_e32 v226, 16, v205
	v_and_b32_e32 v227, 0xffff0000, v205
	v_lshlrev_b32_e32 v228, 16, v206
	v_and_b32_e32 v229, 0xffff0000, v206
	v_lshlrev_b32_e32 v230, 16, v207
	v_and_b32_e32 v231, 0xffff0000, v207
	v_pk_fma_f32 v[68:69], v[68:69], v[132:133], v[224:225]
	v_pk_fma_f32 v[70:71], v[70:71], v[134:135], v[226:227]
	v_pk_fma_f32 v[64:65], v[64:65], v[128:129], v[228:229]
	v_pk_fma_f32 v[66:67], v[66:67], v[130:131], v[230:231]
	v_cvt_pk_bf16_f32 v204, v68, v69
	v_cvt_pk_bf16_f32 v205, v70, v71
	v_cvt_pk_bf16_f32 v206, v64, v65
	v_cvt_pk_bf16_f32 v207, v66, v67
	buffer_store_dwordx4 v[204:207], v181, s[16:19], s74 offen sc1
	s_nop 0
	v_lshl_add_u64 v[192:193], v[192:193], 0, s[10:11]
	global_load_dwordx4 v[204:207], v[192:193], off offset:256 nt
	s_waitcnt vmcnt(10)
	v_lshlrev_b32_e32 v224, 16, v208
	v_and_b32_e32 v225, 0xffff0000, v208
	v_lshlrev_b32_e32 v226, 16, v209
	v_and_b32_e32 v227, 0xffff0000, v209
	v_lshlrev_b32_e32 v228, 16, v210
	v_and_b32_e32 v229, 0xffff0000, v210
	v_lshlrev_b32_e32 v230, 16, v211
	v_and_b32_e32 v231, 0xffff0000, v211
	v_pk_fma_f32 v[60:61], v[60:61], v[184:185], v[224:225]
	v_pk_fma_f32 v[62:63], v[62:63], v[186:187], v[226:227]
	v_pk_fma_f32 v[56:57], v[56:57], v[188:189], v[228:229]
	v_pk_fma_f32 v[58:59], v[58:59], v[190:191], v[230:231]
	v_cvt_pk_bf16_f32 v208, v60, v61
	v_cvt_pk_bf16_f32 v209, v62, v63
	v_cvt_pk_bf16_f32 v210, v56, v57
	v_cvt_pk_bf16_f32 v211, v58, v59
	buffer_store_dwordx4 v[208:211], v181, s[16:19], 0 offen offset:256 sc1
	s_nop 0
	v_lshl_add_u64 v[192:193], v[192:193], 0, s[10:11]
	global_load_dwordx4 v[208:211], v[192:193], off offset:256 nt
	s_waitcnt vmcnt(10)
	v_lshlrev_b32_e32 v224, 16, v212
	v_and_b32_e32 v225, 0xffff0000, v212
	v_lshlrev_b32_e32 v226, 16, v213
	v_and_b32_e32 v227, 0xffff0000, v213
	v_lshlrev_b32_e32 v228, 16, v214
	v_and_b32_e32 v229, 0xffff0000, v214
	v_lshlrev_b32_e32 v230, 16, v215
	v_and_b32_e32 v231, 0xffff0000, v215
	v_pk_fma_f32 v[52:53], v[52:53], v[184:185], v[224:225]
	v_pk_fma_f32 v[54:55], v[54:55], v[186:187], v[226:227]
	v_pk_fma_f32 v[48:49], v[48:49], v[188:189], v[228:229]
	v_pk_fma_f32 v[50:51], v[50:51], v[190:191], v[230:231]
	v_cvt_pk_bf16_f32 v212, v52, v53
	v_cvt_pk_bf16_f32 v213, v54, v55
	v_cvt_pk_bf16_f32 v214, v48, v49
	v_cvt_pk_bf16_f32 v215, v50, v51
	buffer_store_dwordx4 v[212:215], v181, s[16:19], s14 offen offset:256 sc1
	s_nop 0
	v_lshl_add_u64 v[192:193], v[192:193], 0, s[10:11]
	global_load_dwordx4 v[212:215], v[192:193], off offset:256 nt
	s_waitcnt vmcnt(10)
	v_lshlrev_b32_e32 v224, 16, v216
	v_and_b32_e32 v225, 0xffff0000, v216
	v_lshlrev_b32_e32 v226, 16, v217
	v_and_b32_e32 v227, 0xffff0000, v217
	v_lshlrev_b32_e32 v228, 16, v218
	v_and_b32_e32 v229, 0xffff0000, v218
	v_lshlrev_b32_e32 v230, 16, v219
	v_and_b32_e32 v231, 0xffff0000, v219
	v_pk_fma_f32 v[44:45], v[44:45], v[184:185], v[224:225]
	v_pk_fma_f32 v[46:47], v[46:47], v[186:187], v[226:227]
	v_pk_fma_f32 v[40:41], v[40:41], v[188:189], v[228:229]
	v_pk_fma_f32 v[42:43], v[42:43], v[190:191], v[230:231]
	v_cvt_pk_bf16_f32 v216, v44, v45
	v_cvt_pk_bf16_f32 v217, v46, v47
	v_cvt_pk_bf16_f32 v218, v40, v41
	v_cvt_pk_bf16_f32 v219, v42, v43
	buffer_store_dwordx4 v[216:219], v181, s[16:19], s15 offen offset:256 sc1
	s_waitcnt vmcnt(9)
	v_lshlrev_b32_e32 v224, 16, v220
	v_and_b32_e32 v225, 0xffff0000, v220
	v_lshlrev_b32_e32 v226, 16, v221
	v_and_b32_e32 v227, 0xffff0000, v221
	v_lshlrev_b32_e32 v228, 16, v222
	v_and_b32_e32 v229, 0xffff0000, v222
	v_lshlrev_b32_e32 v230, 16, v223
	v_and_b32_e32 v231, 0xffff0000, v223
	v_pk_fma_f32 v[36:37], v[36:37], v[184:185], v[224:225]
	v_pk_fma_f32 v[38:39], v[38:39], v[186:187], v[226:227]
	v_pk_fma_f32 v[32:33], v[32:33], v[188:189], v[228:229]
	v_pk_fma_f32 v[34:35], v[34:35], v[190:191], v[230:231]
	v_cvt_pk_bf16_f32 v220, v36, v37
	v_cvt_pk_bf16_f32 v221, v38, v39
	v_cvt_pk_bf16_f32 v222, v32, v33
	v_cvt_pk_bf16_f32 v223, v34, v35
	buffer_store_dwordx4 v[220:223], v181, s[16:19], s23 offen offset:256 sc1
	s_waitcnt vmcnt(8)
	v_lshlrev_b32_e32 v224, 16, v200
	v_and_b32_e32 v225, 0xffff0000, v200
	v_lshlrev_b32_e32 v226, 16, v201
	v_and_b32_e32 v227, 0xffff0000, v201
	v_lshlrev_b32_e32 v228, 16, v202
	v_and_b32_e32 v229, 0xffff0000, v202
	v_lshlrev_b32_e32 v230, 16, v203
	v_and_b32_e32 v231, 0xffff0000, v203
	v_pk_fma_f32 v[28:29], v[28:29], v[184:185], v[224:225]
	v_pk_fma_f32 v[30:31], v[30:31], v[186:187], v[226:227]
	v_pk_fma_f32 v[24:25], v[24:25], v[188:189], v[228:229]
	v_pk_fma_f32 v[26:27], v[26:27], v[190:191], v[230:231]
	v_cvt_pk_bf16_f32 v200, v28, v29
	v_cvt_pk_bf16_f32 v201, v30, v31
	v_cvt_pk_bf16_f32 v202, v24, v25
	v_cvt_pk_bf16_f32 v203, v26, v27
	buffer_store_dwordx4 v[200:203], v181, s[16:19], s24 offen offset:256 sc1
	s_waitcnt vmcnt(7)
	v_lshlrev_b32_e32 v224, 16, v204
	v_and_b32_e32 v225, 0xffff0000, v204
	v_lshlrev_b32_e32 v226, 16, v205
	v_and_b32_e32 v227, 0xffff0000, v205
	v_lshlrev_b32_e32 v228, 16, v206
	v_and_b32_e32 v229, 0xffff0000, v206
	v_lshlrev_b32_e32 v230, 16, v207
	v_and_b32_e32 v231, 0xffff0000, v207
	v_pk_fma_f32 v[20:21], v[20:21], v[184:185], v[224:225]
	v_pk_fma_f32 v[22:23], v[22:23], v[186:187], v[226:227]
	v_pk_fma_f32 v[16:17], v[16:17], v[188:189], v[228:229]
	v_pk_fma_f32 v[18:19], v[18:19], v[190:191], v[230:231]
	v_cvt_pk_bf16_f32 v204, v20, v21
	v_cvt_pk_bf16_f32 v205, v22, v23
	v_cvt_pk_bf16_f32 v206, v16, v17
	v_cvt_pk_bf16_f32 v207, v18, v19
	buffer_store_dwordx4 v[204:207], v181, s[16:19], s32 offen offset:256 sc1
	s_waitcnt vmcnt(6)
	v_lshlrev_b32_e32 v224, 16, v208
	v_and_b32_e32 v225, 0xffff0000, v208
	v_lshlrev_b32_e32 v226, 16, v209
	v_and_b32_e32 v227, 0xffff0000, v209
	v_lshlrev_b32_e32 v228, 16, v210
	v_and_b32_e32 v229, 0xffff0000, v210
	v_lshlrev_b32_e32 v230, 16, v211
	v_and_b32_e32 v231, 0xffff0000, v211
	v_pk_fma_f32 v[12:13], v[12:13], v[184:185], v[224:225]
	v_pk_fma_f32 v[14:15], v[14:15], v[186:187], v[226:227]
	v_pk_fma_f32 v[8:9], v[8:9], v[188:189], v[228:229]
	v_pk_fma_f32 v[10:11], v[10:11], v[190:191], v[230:231]
	v_cvt_pk_bf16_f32 v208, v12, v13
	v_cvt_pk_bf16_f32 v209, v14, v15
	v_cvt_pk_bf16_f32 v210, v8, v9
	v_cvt_pk_bf16_f32 v211, v10, v11
	buffer_store_dwordx4 v[208:211], v181, s[16:19], s55 offen offset:256 sc1
	s_waitcnt vmcnt(5)
	v_lshlrev_b32_e32 v224, 16, v212
	v_and_b32_e32 v225, 0xffff0000, v212
	v_lshlrev_b32_e32 v226, 16, v213
	v_and_b32_e32 v227, 0xffff0000, v213
	v_lshlrev_b32_e32 v228, 16, v214
	v_and_b32_e32 v229, 0xffff0000, v214
	v_lshlrev_b32_e32 v230, 16, v215
	v_and_b32_e32 v231, 0xffff0000, v215
	v_pk_fma_f32 v[4:5], v[4:5], v[184:185], v[224:225]
	v_pk_fma_f32 v[6:7], v[6:7], v[186:187], v[226:227]
	v_pk_fma_f32 v[0:1], v[0:1], v[188:189], v[228:229]
	v_pk_fma_f32 v[2:3], v[2:3], v[190:191], v[230:231]
	v_cvt_pk_bf16_f32 v212, v4, v5
	v_cvt_pk_bf16_f32 v213, v6, v7
	v_cvt_pk_bf16_f32 v214, v0, v1
	v_cvt_pk_bf16_f32 v215, v2, v3
	buffer_store_dwordx4 v[212:215], v181, s[16:19], s74 offen offset:256 sc1
	s_mov_b64 s[0:1], -1
	s_and_b64 vcc, exec, s[38:39]
	s_cbranch_vccz .LBB0_1002
	s_waitcnt vmcnt(0)
	s_barrier
	s_and_saveexec_b64 s[0:1], s[92:93]
	s_cbranch_execz .LBB0_998
	s_mov_b64 s[6:7], exec
	v_mbcnt_lo_u32_b32 v0, s6, 0
	v_mbcnt_hi_u32_b32 v0, s7, v0
	v_cmp_eq_u32_e32 vcc, 0, v0
	s_and_saveexec_b64 s[4:5], vcc
	s_cbranch_execz .LBB0_995
	s_ashr_i32 s23, s22, 31
	s_lshl_b64 s[10:11], s[22:23], 2
	s_add_u32 s10, s33, s10
	s_addc_u32 s11, s56, s11
	s_bcnt1_i32_b64 s6, s[6:7]
	v_mov_b32_e32 v1, s6
	global_atomic_add v1, v139, v1, s[10:11] sc0

.LBB0_1010:
	s_andn2_b64 vcc, exec, s[0:1]
	s_cbranch_vccz .LBB0_1012
	s_mov_b32 s24, s22
	s_cmpk_lg_i32 s82, 0x100
	s_cselect_b32 s24, s24, -1
	s_mov_b32 s8, s58
	s_mov_b32 s58, s80
	s_mov_b32 s22, s81
	s_mov_b64 s[4:5], s[52:53]
	s_mov_b64 s[0:1], s[50:51]
	s_mov_b32 s2, s79
	s_branch .LBB0_952
.Lfz_epi:
	s_lshl_b32 s8, s22, 8
	v_add_u32_e32 v180, s8, v165
	v_lshl_or_b32 v160, s58, 8, v169
	v_readlane_b32 s4, v249, 44
	v_readlane_b32 s5, v249, 45
	s_ashr_i32 s0, s22, 3
	s_mul_hi_i32 s1, s0, 0x6000
	s_mulk_i32 s0, 0x6000
	s_add_u32 s0, s64, s0
	s_addc_u32 s1, s65, s1
	v_mov_b32_e32 v161, 0
	v_lshl_add_u32 v158, v180, 10, v160
	v_mov_b32_e32 v159, 0
	v_lshl_add_u64 v[156:157], v[160:161], 2, s[0:1]
	v_lshl_add_u64 v[162:163], v[158:159], 1, s[4:5]
	global_load_dwordx4 v[132:135], v[156:157], off
	global_load_dwordx4 v[128:131], v[156:157], off offset:16
	s_mov_b32 s10, 0x8000
	s_mov_b32 s11, 0
	s_mov_b32 s12, 0x28000
	s_mov_b32 s13, 0
	v_mov_b64_e32 v[192:193], v[162:163]
	global_load_dwordx4 v[200:203], v[192:193], off nt
	v_lshl_add_u64 v[192:193], v[192:193], 0, s[10:11]
	global_load_dwordx4 v[204:207], v[192:193], off nt
	global_load_dwordx4 v[184:187], v[156:157], off offset:512
	global_load_dwordx4 v[188:191], v[156:157], off offset:528
	v_lshl_add_u64 v[192:193], v[192:193], 0, s[10:11]
	global_load_dwordx4 v[208:211], v[192:193], off nt
	v_lshl_add_u64 v[192:193], v[192:193], 0, s[10:11]
	global_load_dwordx4 v[212:215], v[192:193], off nt
	v_lshl_add_u64 v[192:193], v[192:193], 0, s[12:13]
	global_load_dwordx4 v[216:219], v[192:193], off nt
	v_lshl_add_u64 v[192:193], v[192:193], 0, s[10:11]
	global_load_dwordx4 v[220:223], v[192:193], off nt
	s_waitcnt vmcnt(7)
	v_lshlrev_b32_e32 v224, 16, v200
	v_and_b32_e32 v225, 0xffff0000, v200
	v_lshlrev_b32_e32 v226, 16, v201
	v_and_b32_e32 v227, 0xffff0000, v201
	v_lshlrev_b32_e32 v228, 16, v202
	v_and_b32_e32 v229, 0xffff0000, v202
	v_lshlrev_b32_e32 v230, 16, v203
	v_and_b32_e32 v231, 0xffff0000, v203
	v_pk_fma_f32 v[124:125], v[124:125], v[132:133], v[224:225]
	v_pk_fma_f32 v[126:127], v[126:127], v[134:135], v[226:227]
	v_pk_fma_f32 v[120:121], v[120:121], v[128:129], v[228:229]
	v_pk_fma_f32 v[122:123], v[122:123], v[130:131], v[230:231]
	v_lshl_add_u64 v[192:193], v[192:193], 0, s[10:11]
	global_load_dwordx4 v[200:203], v[192:193], off nt
	s_waitcnt vmcnt(7)
	v_lshlrev_b32_e32 v224, 16, v204
	v_and_b32_e32 v225, 0xffff0000, v204
	v_lshlrev_b32_e32 v226, 16, v205
	v_and_b32_e32 v227, 0xffff0000, v205
	v_lshlrev_b32_e32 v228, 16, v206
	v_and_b32_e32 v229, 0xffff0000, v206
	v_lshlrev_b32_e32 v230, 16, v207
	v_and_b32_e32 v231, 0xffff0000, v207
	v_pk_fma_f32 v[116:117], v[116:117], v[132:133], v[224:225]
	v_pk_fma_f32 v[118:119], v[118:119], v[134:135], v[226:227]
	v_pk_fma_f32 v[112:113], v[112:113], v[128:129], v[228:229]
	v_pk_fma_f32 v[114:115], v[114:115], v[130:131], v[230:231]
	v_lshl_add_u64 v[192:193], v[192:193], 0, s[10:11]
	global_load_dwordx4 v[204:207], v[192:193], off nt
	s_waitcnt vmcnt(5)
	v_lshlrev_b32_e32 v224, 16, v208
	v_and_b32_e32 v225, 0xffff0000, v208
	v_lshlrev_b32_e32 v226, 16, v209
	v_and_b32_e32 v227, 0xffff0000, v209
	v_lshlrev_b32_e32 v228, 16, v210
	v_and_b32_e32 v229, 0xffff0000, v210
	v_lshlrev_b32_e32 v230, 16, v211
	v_and_b32_e32 v231, 0xffff0000, v211
	v_pk_fma_f32 v[108:109], v[108:109], v[132:133], v[224:225]
	v_pk_fma_f32 v[110:111], v[110:111], v[134:135], v[226:227]
	v_pk_fma_f32 v[104:105], v[104:105], v[128:129], v[228:229]
	v_pk_fma_f32 v[106:107], v[106:107], v[130:131], v[230:231]
	v_mov_b64_e32 v[192:193], v[162:163]
	global_load_dwordx4 v[208:211], v[192:193], off offset:256 nt
	s_waitcnt vmcnt(5)
	v_lshlrev_b32_e32 v224, 16, v212
	v_and_b32_e32 v225, 0xffff0000, v212
	v_lshlrev_b32_e32 v226, 16, v213
	v_and_b32_e32 v227, 0xffff0000, v213
	v_lshlrev_b32_e32 v228, 16, v214
	v_and_b32_e32 v229, 0xffff0000, v214
	v_lshlrev_b32_e32 v230, 16, v215
	v_and_b32_e32 v231, 0xffff0000, v215
	v_pk_fma_f32 v[100:101], v[100:101], v[132:133], v[224:225]
	v_pk_fma_f32 v[102:103], v[102:103], v[134:135], v[226:227]
	v_pk_fma_f32 v[96:97], v[96:97], v[128:129], v[228:229]
	v_pk_fma_f32 v[98:99], v[98:99], v[130:131], v[230:231]
	v_lshl_add_u64 v[192:193], v[192:193], 0, s[10:11]
	global_load_dwordx4 v[212:215], v[192:193], off offset:256 nt
	s_waitcnt vmcnt(5)
	v_lshlrev_b32_e32 v224, 16, v216
	v_and_b32_e32 v225, 0xffff0000, v216
	v_lshlrev_b32_e32 v226, 16, v217
	v_and_b32_e32 v227, 0xffff0000, v217
	v_lshlrev_b32_e32 v228, 16, v218
	v_and_b32_e32 v229, 0xffff0000, v218
	v_lshlrev_b32_e32 v230, 16, v219
	v_and_b32_e32 v231, 0xffff0000, v219
	v_pk_fma_f32 v[92:93], v[92:93], v[132:133], v[224:225]
	v_pk_fma_f32 v[94:95], v[94:95], v[134:135], v[226:227]
	v_pk_fma_f32 v[88:89], v[88:89], v[128:129], v[228:229]
	v_pk_fma_f32 v[90:91], v[90:91], v[130:131], v[230:231]
	v_lshl_add_u64 v[192:193], v[192:193], 0, s[10:11]
	global_load_dwordx4 v[216:219], v[192:193], off offset:256 nt
	s_waitcnt vmcnt(5)
	v_lshlrev_b32_e32 v224, 16, v220
	v_and_b32_e32 v225, 0xffff0000, v220
	v_lshlrev_b32_e32 v226, 16, v221
	v_and_b32_e32 v227, 0xffff0000, v221
	v_lshlrev_b32_e32 v228, 16, v222
	v_and_b32_e32 v229, 0xffff0000, v222
	v_lshlrev_b32_e32 v230, 16, v223
	v_and_b32_e32 v231, 0xffff0000, v223
	v_pk_fma_f32 v[84:85], v[84:85], v[132:133], v[224:225]
	v_pk_fma_f32 v[86:87], v[86:87], v[134:135], v[226:227]
	v_pk_fma_f32 v[80:81], v[80:81], v[128:129], v[228:229]
	v_pk_fma_f32 v[82:83], v[82:83], v[130:131], v[230:231]
	v_lshl_add_u64 v[192:193], v[192:193], 0, s[10:11]
	global_load_dwordx4 v[220:223], v[192:193], off offset:256 nt
	s_waitcnt vmcnt(5)
	v_lshlrev_b32_e32 v224, 16, v200
	v_and_b32_e32 v225, 0xffff0000, v200
	v_lshlrev_b32_e32 v226, 16, v201
	v_and_b32_e32 v227, 0xffff0000, v201
	v_lshlrev_b32_e32 v228, 16, v202
	v_and_b32_e32 v229, 0xffff0000, v202
	v_lshlrev_b32_e32 v230, 16, v203
	v_and_b32_e32 v231, 0xffff0000, v203
	v_pk_fma_f32 v[76:77], v[76:77], v[132:133], v[224:225]
	v_pk_fma_f32 v[78:79], v[78:79], v[134:135], v[226:227]
	v_pk_fma_f32 v[72:73], v[72:73], v[128:129], v[228:229]
	v_pk_fma_f32 v[74:75], v[74:75], v[130:131], v[230:231]
	v_lshl_add_u64 v[192:193], v[192:193], 0, s[12:13]
	global_load_dwordx4 v[200:203], v[192:193], off offset:256 nt
	s_waitcnt vmcnt(5)
	v_lshlrev_b32_e32 v224, 16, v204
	v_and_b32_e32 v225, 0xffff0000, v204
	v_lshlrev_b32_e32 v226, 16, v205
	v_and_b32_e32 v227, 0xffff0000, v205
	v_lshlrev_b32_e32 v228, 16, v206
	v_and_b32_e32 v229, 0xffff0000, v206
	v_lshlrev_b32_e32 v230, 16, v207
	v_and_b32_e32 v231, 0xffff0000, v207
	v_pk_fma_f32 v[68:69], v[68:69], v[132:133], v[224:225]
	v_pk_fma_f32 v[70:71], v[70:71], v[134:135], v[226:227]
	v_pk_fma_f32 v[64:65], v[64:65], v[128:129], v[228:229]
	v_pk_fma_f32 v[66:67], v[66:67], v[130:131], v[230:231]
	v_lshl_add_u64 v[192:193], v[192:193], 0, s[10:11]
	global_load_dwordx4 v[204:207], v[192:193], off offset:256 nt
	s_waitcnt vmcnt(5)
	v_lshlrev_b32_e32 v224, 16, v208
	v_and_b32_e32 v225, 0xffff0000, v208
	v_lshlrev_b32_e32 v226, 16, v209
	v_and_b32_e32 v227, 0xffff0000, v209
	v_lshlrev_b32_e32 v228, 16, v210
	v_and_b32_e32 v229, 0xffff0000, v210
	v_lshlrev_b32_e32 v230, 16, v211
	v_and_b32_e32 v231, 0xffff0000, v211
	v_pk_fma_f32 v[60:61], v[60:61], v[184:185], v[224:225]
	v_pk_fma_f32 v[62:63], v[62:63], v[186:187], v[226:227]
	v_pk_fma_f32 v[56:57], v[56:57], v[188:189], v[228:229]
	v_pk_fma_f32 v[58:59], v[58:59], v[190:191], v[230:231]
	v_lshl_add_u64 v[192:193], v[192:193], 0, s[10:11]
	global_load_dwordx4 v[208:211], v[192:193], off offset:256 nt
	s_waitcnt vmcnt(5)
	v_lshlrev_b32_e32 v224, 16, v212
	v_and_b32_e32 v225, 0xffff0000, v212
	v_lshlrev_b32_e32 v226, 16, v213
	v_and_b32_e32 v227, 0xffff0000, v213
	v_lshlrev_b32_e32 v228, 16, v214
	v_and_b32_e32 v229, 0xffff0000, v214
	v_lshlrev_b32_e32 v230, 16, v215
	v_and_b32_e32 v231, 0xffff0000, v215
	v_pk_fma_f32 v[52:53], v[52:53], v[184:185], v[224:225]
	v_pk_fma_f32 v[54:55], v[54:55], v[186:187], v[226:227]
	v_pk_fma_f32 v[48:49], v[48:49], v[188:189], v[228:229]
	v_pk_fma_f32 v[50:51], v[50:51], v[190:191], v[230:231]
	v_lshl_add_u64 v[192:193], v[192:193], 0, s[10:11]
	global_load_dwordx4 v[212:215], v[192:193], off offset:256 nt
	s_waitcnt vmcnt(5)
	v_lshlrev_b32_e32 v224, 16, v216
	v_and_b32_e32 v225, 0xffff0000, v216
	v_lshlrev_b32_e32 v226, 16, v217
	v_and_b32_e32 v227, 0xffff0000, v217
	v_lshlrev_b32_e32 v228, 16, v218
	v_and_b32_e32 v229, 0xffff0000, v218
	v_lshlrev_b32_e32 v230, 16, v219
	v_and_b32_e32 v231, 0xffff0000, v219
	v_pk_fma_f32 v[44:45], v[44:45], v[184:185], v[224:225]
	v_pk_fma_f32 v[46:47], v[46:47], v[186:187], v[226:227]
	v_pk_fma_f32 v[40:41], v[40:41], v[188:189], v[228:229]
	v_pk_fma_f32 v[42:43], v[42:43], v[190:191], v[230:231]
	s_waitcnt vmcnt(4)
	v_lshlrev_b32_e32 v224, 16, v220
	v_and_b32_e32 v225, 0xffff0000, v220
	v_lshlrev_b32_e32 v226, 16, v221
	v_and_b32_e32 v227, 0xffff0000, v221
	v_lshlrev_b32_e32 v228, 16, v222
	v_and_b32_e32 v229, 0xffff0000, v222
	v_lshlrev_b32_e32 v230, 16, v223
	v_and_b32_e32 v231, 0xffff0000, v223
	v_pk_fma_f32 v[36:37], v[36:37], v[184:185], v[224:225]
	v_pk_fma_f32 v[38:39], v[38:39], v[186:187], v[226:227]
	v_pk_fma_f32 v[32:33], v[32:33], v[188:189], v[228:229]
	v_pk_fma_f32 v[34:35], v[34:35], v[190:191], v[230:231]
	s_waitcnt vmcnt(3)
	v_lshlrev_b32_e32 v224, 16, v200
	v_and_b32_e32 v225, 0xffff0000, v200
	v_lshlrev_b32_e32 v226, 16, v201
	v_and_b32_e32 v227, 0xffff0000, v201
	v_lshlrev_b32_e32 v228, 16, v202
	v_and_b32_e32 v229, 0xffff0000, v202
	v_lshlrev_b32_e32 v230, 16, v203
	v_and_b32_e32 v231, 0xffff0000, v203
	v_pk_fma_f32 v[28:29], v[28:29], v[184:185], v[224:225]
	v_pk_fma_f32 v[30:31], v[30:31], v[186:187], v[226:227]
	v_pk_fma_f32 v[24:25], v[24:25], v[188:189], v[228:229]
	v_pk_fma_f32 v[26:27], v[26:27], v[190:191], v[230:231]
	s_waitcnt vmcnt(2)
	v_lshlrev_b32_e32 v224, 16, v204
	v_and_b32_e32 v225, 0xffff0000, v204
	v_lshlrev_b32_e32 v226, 16, v205
	v_and_b32_e32 v227, 0xffff0000, v205
	v_lshlrev_b32_e32 v228, 16, v206
	v_and_b32_e32 v229, 0xffff0000, v206
	v_lshlrev_b32_e32 v230, 16, v207
	v_and_b32_e32 v231, 0xffff0000, v207
	v_pk_fma_f32 v[20:21], v[20:21], v[184:185], v[224:225]
	v_pk_fma_f32 v[22:23], v[22:23], v[186:187], v[226:227]
	v_pk_fma_f32 v[16:17], v[16:17], v[188:189], v[228:229]
	v_pk_fma_f32 v[18:19], v[18:19], v[190:191], v[230:231]
	s_waitcnt vmcnt(1)
	v_lshlrev_b32_e32 v224, 16, v208
	v_and_b32_e32 v225, 0xffff0000, v208
	v_lshlrev_b32_e32 v226, 16, v209
	v_and_b32_e32 v227, 0xffff0000, v209
	v_lshlrev_b32_e32 v228, 16, v210
	v_and_b32_e32 v229, 0xffff0000, v210
	v_lshlrev_b32_e32 v230, 16, v211
	v_and_b32_e32 v231, 0xffff0000, v211
	v_pk_fma_f32 v[12:13], v[12:13], v[184:185], v[224:225]
	v_pk_fma_f32 v[14:15], v[14:15], v[186:187], v[226:227]
	v_pk_fma_f32 v[8:9], v[8:9], v[188:189], v[228:229]
	v_pk_fma_f32 v[10:11], v[10:11], v[190:191], v[230:231]
	s_waitcnt vmcnt(0)
	v_lshlrev_b32_e32 v224, 16, v212
	v_and_b32_e32 v225, 0xffff0000, v212
	v_lshlrev_b32_e32 v226, 16, v213
	v_and_b32_e32 v227, 0xffff0000, v213
	v_lshlrev_b32_e32 v228, 16, v214
	v_and_b32_e32 v229, 0xffff0000, v214
	v_lshlrev_b32_e32 v230, 16, v215
	v_and_b32_e32 v231, 0xffff0000, v215
	v_pk_fma_f32 v[4:5], v[4:5], v[184:185], v[224:225]
	v_pk_fma_f32 v[6:7], v[6:7], v[186:187], v[226:227]
	v_pk_fma_f32 v[0:1], v[0:1], v[188:189], v[228:229]
	v_pk_fma_f32 v[2:3], v[2:3], v[190:191], v[230:231]
	s_nop 1
	v_lshl_add_u64 v[156:157], v[160:161], 2, s[84:85]
	global_load_dwordx4 v[132:135], v[156:157], off
	global_load_dwordx4 v[128:131], v[156:157], off offset:16
	global_load_dwordx4 v[184:187], v[156:157], off offset:512
	global_load_dwordx4 v[188:191], v[156:157], off offset:528
	v_pk_mul_f32 v[240:241], v[124:125], v[124:125]
	v_pk_mul_f32 v[244:245], v[116:117], v[116:117]
	v_pk_fma_f32 v[240:241], v[126:127], v[126:127], v[240:241]
	v_pk_fma_f32 v[244:245], v[118:119], v[118:119], v[244:245]
	v_pk_fma_f32 v[240:241], v[120:121], v[120:121], v[240:241]
	v_pk_fma_f32 v[244:245], v[112:113], v[112:113], v[244:245]
	v_pk_fma_f32 v[240:241], v[122:123], v[122:123], v[240:241]
	v_pk_fma_f32 v[244:245], v[114:115], v[114:115], v[244:245]
	v_pk_fma_f32 v[240:241], v[60:61], v[60:61], v[240:241]
	v_pk_fma_f32 v[244:245], v[52:53], v[52:53], v[244:245]
	v_pk_fma_f32 v[240:241], v[62:63], v[62:63], v[240:241]
	v_pk_fma_f32 v[244:245], v[54:55], v[54:55], v[244:245]
	v_pk_fma_f32 v[240:241], v[56:57], v[56:57], v[240:241]
	v_pk_fma_f32 v[244:245], v[48:49], v[48:49], v[244:245]
	v_pk_fma_f32 v[240:241], v[58:59], v[58:59], v[240:241]
	v_pk_fma_f32 v[244:245], v[50:51], v[50:51], v[244:245]
	v_add_f32_e32 v232, v240, v241
	v_add_f32_e32 v233, v244, v245
	v_pk_mul_f32 v[240:241], v[108:109], v[108:109]
	v_pk_mul_f32 v[244:245], v[100:101], v[100:101]
	v_pk_fma_f32 v[240:241], v[110:111], v[110:111], v[240:241]
	v_pk_fma_f32 v[244:245], v[102:103], v[102:103], v[244:245]
	v_pk_fma_f32 v[240:241], v[104:105], v[104:105], v[240:241]
	v_pk_fma_f32 v[244:245], v[96:97], v[96:97], v[244:245]
	v_pk_fma_f32 v[240:241], v[106:107], v[106:107], v[240:241]
	v_pk_fma_f32 v[244:245], v[98:99], v[98:99], v[244:245]
	v_pk_fma_f32 v[240:241], v[44:45], v[44:45], v[240:241]
	v_pk_fma_f32 v[244:245], v[36:37], v[36:37], v[244:245]
	v_pk_fma_f32 v[240:241], v[46:47], v[46:47], v[240:241]
	v_pk_fma_f32 v[244:245], v[38:39], v[38:39], v[244:245]
	v_pk_fma_f32 v[240:241], v[40:41], v[40:41], v[240:241]
	v_pk_fma_f32 v[244:245], v[32:33], v[32:33], v[244:245]
	v_pk_fma_f32 v[240:241], v[42:43], v[42:43], v[240:241]
	v_pk_fma_f32 v[244:245], v[34:35], v[34:35], v[244:245]
	v_add_f32_e32 v234, v240, v241
	v_add_f32_e32 v235, v244, v245
	v_pk_mul_f32 v[240:241], v[92:93], v[92:93]
	v_pk_mul_f32 v[244:245], v[84:85], v[84:85]
	v_pk_fma_f32 v[240:241], v[94:95], v[94:95], v[240:241]
	v_pk_fma_f32 v[244:245], v[86:87], v[86:87], v[244:245]
	v_pk_fma_f32 v[240:241], v[88:89], v[88:89], v[240:241]
	v_pk_fma_f32 v[244:245], v[80:81], v[80:81], v[244:245]
	v_pk_fma_f32 v[240:241], v[90:91], v[90:91], v[240:241]
	v_pk_fma_f32 v[244:245], v[82:83], v[82:83], v[244:245]
	v_pk_fma_f32 v[240:241], v[28:29], v[28:29], v[240:241]
	v_pk_fma_f32 v[244:245], v[20:21], v[20:21], v[244:245]
	v_pk_fma_f32 v[240:241], v[30:31], v[30:31], v[240:241]
	v_pk_fma_f32 v[244:245], v[22:23], v[22:23], v[244:245]
	v_pk_fma_f32 v[240:241], v[24:25], v[24:25], v[240:241]
	v_pk_fma_f32 v[244:245], v[16:17], v[16:17], v[244:245]
	v_pk_fma_f32 v[240:241], v[26:27], v[26:27], v[240:241]
	v_pk_fma_f32 v[244:245], v[18:19], v[18:19], v[244:245]
	v_add_f32_e32 v236, v240, v241
	v_add_f32_e32 v237, v244, v245
	v_pk_mul_f32 v[240:241], v[76:77], v[76:77]
	v_pk_mul_f32 v[244:245], v[68:69], v[68:69]
	v_pk_fma_f32 v[240:241], v[78:79], v[78:79], v[240:241]
	v_pk_fma_f32 v[244:245], v[70:71], v[70:71], v[244:245]
	v_pk_fma_f32 v[240:241], v[72:73], v[72:73], v[240:241]
	v_pk_fma_f32 v[244:245], v[64:65], v[64:65], v[244:245]
	v_pk_fma_f32 v[240:241], v[74:75], v[74:75], v[240:241]
	v_pk_fma_f32 v[244:245], v[66:67], v[66:67], v[244:245]
	v_pk_fma_f32 v[240:241], v[12:13], v[12:13], v[240:241]
	v_pk_fma_f32 v[244:245], v[4:5], v[4:5], v[244:245]
	v_pk_fma_f32 v[240:241], v[14:15], v[14:15], v[240:241]
	v_pk_fma_f32 v[244:245], v[6:7], v[6:7], v[244:245]
	v_pk_fma_f32 v[240:241], v[8:9], v[8:9], v[240:241]
	v_pk_fma_f32 v[244:245], v[0:1], v[0:1], v[244:245]
	v_pk_fma_f32 v[240:241], v[10:11], v[10:11], v[240:241]
	v_pk_fma_f32 v[244:245], v[2:3], v[2:3], v[244:245]
	v_add_f32_e32 v238, v240, v241
	v_add_f32_e32 v239, v244, v245
	v_xor_b32_e32 v242, 16, v199
	v_xor_b32_e32 v243, 32, v199
	v_lshlrev_b32_e32 v242, 2, v242
	v_lshlrev_b32_e32 v243, 2, v243
	ds_bpermute_b32 v224, v242, v232
	ds_bpermute_b32 v225, v242, v233
	ds_bpermute_b32 v226, v242, v234
	ds_bpermute_b32 v227, v242, v235
	ds_bpermute_b32 v228, v242, v236
	ds_bpermute_b32 v229, v242, v237
	ds_bpermute_b32 v230, v242, v238
	ds_bpermute_b32 v231, v242, v239
	s_waitcnt lgkmcnt(7)
	v_add_f32_e32 v232, v232, v224
	s_waitcnt lgkmcnt(6)
	v_add_f32_e32 v233, v233, v225
	s_waitcnt lgkmcnt(5)
	v_add_f32_e32 v234, v234, v226
	s_waitcnt lgkmcnt(4)
	v_add_f32_e32 v235, v235, v227
	s_waitcnt lgkmcnt(3)
	v_add_f32_e32 v236, v236, v228
	s_waitcnt lgkmcnt(2)
	v_add_f32_e32 v237, v237, v229
	s_waitcnt lgkmcnt(1)
	v_add_f32_e32 v238, v238, v230
	s_waitcnt lgkmcnt(0)
	v_add_f32_e32 v239, v239, v231
	ds_bpermute_b32 v224, v243, v232
	ds_bpermute_b32 v225, v243, v233
	ds_bpermute_b32 v226, v243, v234
	ds_bpermute_b32 v227, v243, v235
	ds_bpermute_b32 v228, v243, v236
	ds_bpermute_b32 v229, v243, v237
	ds_bpermute_b32 v230, v243, v238
	ds_bpermute_b32 v231, v243, v239
	s_waitcnt lgkmcnt(7)
	v_add_f32_e32 v232, v232, v224
	s_waitcnt lgkmcnt(6)
	v_add_f32_e32 v233, v233, v225
	s_waitcnt lgkmcnt(5)
	v_add_f32_e32 v234, v234, v226
	s_waitcnt lgkmcnt(4)
	v_add_f32_e32 v235, v235, v227
	s_waitcnt lgkmcnt(3)
	v_add_f32_e32 v236, v236, v228
	s_waitcnt lgkmcnt(2)
	v_add_f32_e32 v237, v237, v229
	s_waitcnt lgkmcnt(1)
	v_add_f32_e32 v238, v238, v230
	s_waitcnt lgkmcnt(0)
	v_add_f32_e32 v239, v239, v231
	s_add_u32 s10, s88, 0x1d00000
	s_addc_u32 s11, s89, 0
	v_lshlrev_b32_e32 v244, 6, v180
	v_bfe_u32 v245, v169, 5, 2
	s_lshl_b32 s12, s58, 2
	v_add_u32_e32 v245, s12, v245
	v_lshl_add_u32 v244, v245, 2, v244
	v_mov_b32_e32 v245, 0
	v_lshl_add_u64 v[246:247], v[244:245], 0, s[10:11]
	s_mov_b64 s[12:13], 0x2000
	v_lshl_add_u64 v[194:195], v[246:247], 0, s[12:13]
	v_cmp_gt_u32_e32 vcc, 16, v199
	s_and_saveexec_b64 s[14:15], vcc
	global_store_dword v[246:247], v232, off
	global_store_dword v[246:247], v233, off offset:1024
	global_store_dword v[246:247], v234, off offset:2048
	global_store_dword v[246:247], v235, off offset:3072
	global_store_dword v[194:195], v236, off
	global_store_dword v[194:195], v237, off offset:1024
	global_store_dword v[194:195], v238, off offset:2048
	global_store_dword v[194:195], v239, off offset:3072
	s_or_b64 exec, exec, s[14:15]
	s_waitcnt vmcnt(0)
	s_barrier
	s_and_saveexec_b64 s[0:1], s[92:93]
	s_cbranch_execz .Lfz_sdone
	s_ashr_i32 s23, s22, 31
	s_lshl_b64 s[14:15], s[22:23], 2
	s_add_u32 s14, s33, s14
	s_addc_u32 s15, s56, s15
	v_mov_b32_e32 v244, 1
	global_atomic_add v139, v244, s[14:15]
	s_mov_b32 s12, 0x40000
.Lfz_poll:
	global_load_dword v244, v139, s[14:15] sc1
	s_waitcnt vmcnt(0)
	v_cmp_lt_u32_e32 vcc, 3, v244
	s_cbranch_vccnz .Lfz_pok
	s_sleep 1
	s_add_i32 s12, s12, -1
	s_cmp_lg_u32 s12, 0
	s_cbranch_scc1 .Lfz_poll

.Lfz_sdone:
	s_or_b64 exec, exec, s[0:1]
	s_barrier
	v_lshlrev_b32_e32 v244, 6, v180
	v_lshrrev_b32_e32 v245, 4, v199
	v_lshl_add_u32 v244, v245, 4, v244
	v_mov_b32_e32 v245, 0
	v_lshl_add_u64 v[246:247], v[244:245], 0, s[10:11]
	s_mov_b64 s[12:13], 0x2000
	v_lshl_add_u64 v[194:195], v[246:247], 0, s[12:13]
	global_load_dwordx4 v[200:203], v[246:247], off
	global_load_dwordx4 v[204:207], v[246:247], off offset:1024
	global_load_dwordx4 v[208:211], v[246:247], off offset:2048
	global_load_dwordx4 v[212:215], v[246:247], off offset:3072
	global_load_dwordx4 v[216:219], v[194:195], off
	global_load_dwordx4 v[220:223], v[194:195], off offset:1024
	global_load_dwordx4 v[224:227], v[194:195], off offset:2048
	global_load_dwordx4 v[228:231], v[194:195], off offset:3072
	s_waitcnt vmcnt(7)
	v_add_f32_e32 v200, v200, v201
	v_add_f32_e32 v202, v202, v203
	v_add_f32_e32 v232, v200, v202
	s_waitcnt vmcnt(6)
	v_add_f32_e32 v204, v204, v205
	v_add_f32_e32 v206, v206, v207
	v_add_f32_e32 v233, v204, v206
	s_waitcnt vmcnt(5)
	v_add_f32_e32 v208, v208, v209
	v_add_f32_e32 v210, v210, v211
	v_add_f32_e32 v234, v208, v210
	s_waitcnt vmcnt(4)
	v_add_f32_e32 v212, v212, v213
	v_add_f32_e32 v214, v214, v215
	v_add_f32_e32 v235, v212, v214
	s_waitcnt vmcnt(3)
	v_add_f32_e32 v216, v216, v217
	v_add_f32_e32 v218, v218, v219
	v_add_f32_e32 v236, v216, v218
	s_waitcnt vmcnt(2)
	v_add_f32_e32 v220, v220, v221
	v_add_f32_e32 v222, v222, v223
	v_add_f32_e32 v237, v220, v222
	s_waitcnt vmcnt(1)
	v_add_f32_e32 v224, v224, v225
	v_add_f32_e32 v226, v226, v227
	v_add_f32_e32 v238, v224, v226
	s_waitcnt vmcnt(0)
	v_add_f32_e32 v228, v228, v229
	v_add_f32_e32 v230, v230, v231
	v_add_f32_e32 v239, v228, v230
	ds_bpermute_b32 v224, v242, v232
	ds_bpermute_b32 v225, v242, v233
	ds_bpermute_b32 v226, v242, v234
	ds_bpermute_b32 v227, v242, v235
	ds_bpermute_b32 v228, v242, v236
	ds_bpermute_b32 v229, v242, v237
	ds_bpermute_b32 v230, v242, v238
	ds_bpermute_b32 v231, v242, v239
	s_waitcnt lgkmcnt(7)
	v_add_f32_e32 v232, v232, v224
	s_waitcnt lgkmcnt(6)
	v_add_f32_e32 v233, v233, v225
	s_waitcnt lgkmcnt(5)
	v_add_f32_e32 v234, v234, v226
	s_waitcnt lgkmcnt(4)
	v_add_f32_e32 v235, v235, v227
	s_waitcnt lgkmcnt(3)
	v_add_f32_e32 v236, v236, v228
	s_waitcnt lgkmcnt(2)
	v_add_f32_e32 v237, v237, v229
	s_waitcnt lgkmcnt(1)
	v_add_f32_e32 v238, v238, v230
	s_waitcnt lgkmcnt(0)
	v_add_f32_e32 v239, v239, v231
	ds_bpermute_b32 v224, v243, v232
	ds_bpermute_b32 v225, v243, v233
	ds_bpermute_b32 v226, v243, v234
	ds_bpermute_b32 v227, v243, v235
	ds_bpermute_b32 v228, v243, v236
	ds_bpermute_b32 v229, v243, v237
	ds_bpermute_b32 v230, v243, v238
	ds_bpermute_b32 v231, v243, v239
	s_waitcnt lgkmcnt(7)
	v_add_f32_e32 v232, v232, v224
	s_waitcnt lgkmcnt(6)
	v_add_f32_e32 v233, v233, v225
	s_waitcnt lgkmcnt(5)
	v_add_f32_e32 v234, v234, v226
	s_waitcnt lgkmcnt(4)
	v_add_f32_e32 v235, v235, v227
	s_waitcnt lgkmcnt(3)
	v_add_f32_e32 v236, v236, v228
	s_waitcnt lgkmcnt(2)
	v_add_f32_e32 v237, v237, v229
	s_waitcnt lgkmcnt(1)
	v_add_f32_e32 v238, v238, v230
	s_waitcnt lgkmcnt(0)
	v_add_f32_e32 v239, v239, v231
	v_mul_f32_e32 v232, 0x3a800000, v232
	v_mul_f32_e32 v233, 0x3a800000, v233
	v_mul_f32_e32 v234, 0x3a800000, v234
	v_mul_f32_e32 v235, 0x3a800000, v235
	v_mul_f32_e32 v236, 0x3a800000, v236
	v_mul_f32_e32 v237, 0x3a800000, v237
	v_mul_f32_e32 v238, 0x3a800000, v238
	v_mul_f32_e32 v239, 0x3a800000, v239
	v_add_f32_e32 v232, 0x358637bd, v232
	v_add_f32_e32 v233, 0x358637bd, v233
	v_add_f32_e32 v234, 0x358637bd, v234
	v_add_f32_e32 v235, 0x358637bd, v235
	v_add_f32_e32 v236, 0x358637bd, v236
	v_add_f32_e32 v237, 0x358637bd, v237
	v_add_f32_e32 v238, 0x358637bd, v238
	v_add_f32_e32 v239, 0x358637bd, v239
	v_rsq_f32_e32 v224, v232
	v_rsq_f32_e32 v225, v233
	v_rsq_f32_e32 v226, v234
	v_rsq_f32_e32 v227, v235
	v_rsq_f32_e32 v228, v236
	v_rsq_f32_e32 v229, v237
	v_rsq_f32_e32 v230, v238
	v_rsq_f32_e32 v231, v239
	s_nop 0
	v_mul_f32_e32 v232, v232, v224
	v_mul_f32_e32 v233, v233, v225
	v_mul_f32_e32 v234, v234, v226
	v_mul_f32_e32 v235, v235, v227
	v_mul_f32_e32 v236, v236, v228
	v_mul_f32_e32 v237, v237, v229
	v_mul_f32_e32 v238, v238, v230
	v_mul_f32_e32 v239, v239, v231
	v_mul_f32_e32 v200, 0.5, v224
	v_mul_f32_e32 v201, 0.5, v225
	v_mul_f32_e32 v202, 0.5, v226
	v_mul_f32_e32 v203, 0.5, v227
	v_mul_f32_e32 v204, 0.5, v228
	v_mul_f32_e32 v205, 0.5, v229
	v_mul_f32_e32 v206, 0.5, v230
	v_mul_f32_e32 v207, 0.5, v231
	v_fma_f32 v232, -v232, v200, 0.5
	v_fma_f32 v233, -v233, v201, 0.5
	v_fma_f32 v234, -v234, v202, 0.5
	v_fma_f32 v235, -v235, v203, 0.5
	v_fma_f32 v236, -v236, v204, 0.5
	v_fma_f32 v237, -v237, v205, 0.5
	v_fma_f32 v238, -v238, v206, 0.5
	v_fma_f32 v239, -v239, v207, 0.5
	v_fma_f32 v224, v224, v232, v224
	v_fma_f32 v225, v225, v233, v225
	v_fma_f32 v226, v226, v234, v226
	v_fma_f32 v227, v227, v235, v227
	v_fma_f32 v228, v228, v236, v228
	v_fma_f32 v229, v229, v237, v229
	v_fma_f32 v230, v230, v238, v230
	v_fma_f32 v231, v231, v239, v231
	v_mov_b32_e32 v246, v231
	v_mov_b32_e32 v244, v230
	v_mov_b32_e32 v242, v229
	v_mov_b32_e32 v240, v228
	v_mov_b32_e32 v238, v227
	v_mov_b32_e32 v236, v226
	v_mov_b32_e32 v234, v225
	v_mov_b32_e32 v232, v224
	s_waitcnt vmcnt(0)
	v_lshl_add_u64 v[192:193], v[158:159], 2, s[86:87]
	s_mov_b64 s[12:13], 0x10000
	s_mov_b64 s[14:15], 0x50000
	v_pk_mul_f32 v[124:125], v[124:125], v[232:233] op_sel_hi:[1,0]
	v_pk_mul_f32 v[126:127], v[126:127], v[232:233] op_sel_hi:[1,0]
	v_pk_mul_f32 v[120:121], v[120:121], v[232:233] op_sel_hi:[1,0]
	v_pk_mul_f32 v[122:123], v[122:123], v[232:233] op_sel_hi:[1,0]
	v_pk_mul_f32 v[124:125], v[124:125], v[132:133]
	v_pk_mul_f32 v[126:127], v[126:127], v[134:135]
	v_pk_mul_f32 v[120:121], v[120:121], v[128:129]
	v_pk_mul_f32 v[122:123], v[122:123], v[130:131]
	global_store_dwordx4 v[192:193], v[124:127], off nt
	global_store_dwordx4 v[192:193], v[120:123], off offset:16 nt
	v_pk_mul_f32 v[60:61], v[60:61], v[232:233] op_sel_hi:[1,0]
	v_pk_mul_f32 v[62:63], v[62:63], v[232:233] op_sel_hi:[1,0]
	v_pk_mul_f32 v[56:57], v[56:57], v[232:233] op_sel_hi:[1,0]
	v_pk_mul_f32 v[58:59], v[58:59], v[232:233] op_sel_hi:[1,0]
	v_pk_mul_f32 v[60:61], v[60:61], v[184:185]
	v_pk_mul_f32 v[62:63], v[62:63], v[186:187]
	v_pk_mul_f32 v[56:57], v[56:57], v[188:189]
	v_pk_mul_f32 v[58:59], v[58:59], v[190:191]
	global_store_dwordx4 v[192:193], v[60:63], off offset:512 nt
	global_store_dwordx4 v[192:193], v[56:59], off offset:528 nt
	v_lshl_add_u64 v[192:193], v[192:193], 0, s[12:13]
	v_pk_mul_f32 v[116:117], v[116:117], v[234:235] op_sel_hi:[1,0]
	v_pk_mul_f32 v[118:119], v[118:119], v[234:235] op_sel_hi:[1,0]
	v_pk_mul_f32 v[112:113], v[112:113], v[234:235] op_sel_hi:[1,0]
	v_pk_mul_f32 v[114:115], v[114:115], v[234:235] op_sel_hi:[1,0]
	v_pk_mul_f32 v[116:117], v[116:117], v[132:133]
	v_pk_mul_f32 v[118:119], v[118:119], v[134:135]
	v_pk_mul_f32 v[112:113], v[112:113], v[128:129]
	v_pk_mul_f32 v[114:115], v[114:115], v[130:131]
	global_store_dwordx4 v[192:193], v[116:119], off nt
	global_store_dwordx4 v[192:193], v[112:115], off offset:16 nt
	v_pk_mul_f32 v[52:53], v[52:53], v[234:235] op_sel_hi:[1,0]
	v_pk_mul_f32 v[54:55], v[54:55], v[234:235] op_sel_hi:[1,0]
	v_pk_mul_f32 v[48:49], v[48:49], v[234:235] op_sel_hi:[1,0]
	v_pk_mul_f32 v[50:51], v[50:51], v[234:235] op_sel_hi:[1,0]
	v_pk_mul_f32 v[52:53], v[52:53], v[184:185]
	v_pk_mul_f32 v[54:55], v[54:55], v[186:187]
	v_pk_mul_f32 v[48:49], v[48:49], v[188:189]
	v_pk_mul_f32 v[50:51], v[50:51], v[190:191]
	global_store_dwordx4 v[192:193], v[52:55], off offset:512 nt
	global_store_dwordx4 v[192:193], v[48:51], off offset:528 nt
	v_lshl_add_u64 v[192:193], v[192:193], 0, s[12:13]
	v_pk_mul_f32 v[108:109], v[108:109], v[236:237] op_sel_hi:[1,0]
	v_pk_mul_f32 v[110:111], v[110:111], v[236:237] op_sel_hi:[1,0]
	v_pk_mul_f32 v[104:105], v[104:105], v[236:237] op_sel_hi:[1,0]
	v_pk_mul_f32 v[106:107], v[106:107], v[236:237] op_sel_hi:[1,0]
	v_pk_mul_f32 v[108:109], v[108:109], v[132:133]
	v_pk_mul_f32 v[110:111], v[110:111], v[134:135]
	v_pk_mul_f32 v[104:105], v[104:105], v[128:129]
	v_pk_mul_f32 v[106:107], v[106:107], v[130:131]
	global_store_dwordx4 v[192:193], v[108:111], off nt
	global_store_dwordx4 v[192:193], v[104:107], off offset:16 nt
	v_pk_mul_f32 v[44:45], v[44:45], v[236:237] op_sel_hi:[1,0]
	v_pk_mul_f32 v[46:47], v[46:47], v[236:237] op_sel_hi:[1,0]
	v_pk_mul_f32 v[40:41], v[40:41], v[236:237] op_sel_hi:[1,0]
	v_pk_mul_f32 v[42:43], v[42:43], v[236:237] op_sel_hi:[1,0]
	v_pk_mul_f32 v[44:45], v[44:45], v[184:185]
	v_pk_mul_f32 v[46:47], v[46:47], v[186:187]
	v_pk_mul_f32 v[40:41], v[40:41], v[188:189]
	v_pk_mul_f32 v[42:43], v[42:43], v[190:191]
	global_store_dwordx4 v[192:193], v[44:47], off offset:512 nt
	global_store_dwordx4 v[192:193], v[40:43], off offset:528 nt
	v_lshl_add_u64 v[192:193], v[192:193], 0, s[12:13]
	v_pk_mul_f32 v[100:101], v[100:101], v[238:239] op_sel_hi:[1,0]
	v_pk_mul_f32 v[102:103], v[102:103], v[238:239] op_sel_hi:[1,0]
	v_pk_mul_f32 v[96:97], v[96:97], v[238:239] op_sel_hi:[1,0]
	v_pk_mul_f32 v[98:99], v[98:99], v[238:239] op_sel_hi:[1,0]
	v_pk_mul_f32 v[100:101], v[100:101], v[132:133]
	v_pk_mul_f32 v[102:103], v[102:103], v[134:135]
	v_pk_mul_f32 v[96:97], v[96:97], v[128:129]
	v_pk_mul_f32 v[98:99], v[98:99], v[130:131]
	global_store_dwordx4 v[192:193], v[100:103], off nt
	global_store_dwordx4 v[192:193], v[96:99], off offset:16 nt
	v_pk_mul_f32 v[36:37], v[36:37], v[238:239] op_sel_hi:[1,0]
	v_pk_mul_f32 v[38:39], v[38:39], v[238:239] op_sel_hi:[1,0]
	v_pk_mul_f32 v[32:33], v[32:33], v[238:239] op_sel_hi:[1,0]
	v_pk_mul_f32 v[34:35], v[34:35], v[238:239] op_sel_hi:[1,0]
	v_pk_mul_f32 v[36:37], v[36:37], v[184:185]
	v_pk_mul_f32 v[38:39], v[38:39], v[186:187]
	v_pk_mul_f32 v[32:33], v[32:33], v[188:189]
	v_pk_mul_f32 v[34:35], v[34:35], v[190:191]
	global_store_dwordx4 v[192:193], v[36:39], off offset:512 nt
	global_store_dwordx4 v[192:193], v[32:35], off offset:528 nt
	v_lshl_add_u64 v[192:193], v[192:193], 0, s[14:15]
	v_pk_mul_f32 v[92:93], v[92:93], v[240:241] op_sel_hi:[1,0]
	v_pk_mul_f32 v[94:95], v[94:95], v[240:241] op_sel_hi:[1,0]
	v_pk_mul_f32 v[88:89], v[88:89], v[240:241] op_sel_hi:[1,0]
	v_pk_mul_f32 v[90:91], v[90:91], v[240:241] op_sel_hi:[1,0]
	v_pk_mul_f32 v[92:93], v[92:93], v[132:133]
	v_pk_mul_f32 v[94:95], v[94:95], v[134:135]
	v_pk_mul_f32 v[88:89], v[88:89], v[128:129]
	v_pk_mul_f32 v[90:91], v[90:91], v[130:131]
	global_store_dwordx4 v[192:193], v[92:95], off nt
	global_store_dwordx4 v[192:193], v[88:91], off offset:16 nt
	v_pk_mul_f32 v[28:29], v[28:29], v[240:241] op_sel_hi:[1,0]
	v_pk_mul_f32 v[30:31], v[30:31], v[240:241] op_sel_hi:[1,0]
	v_pk_mul_f32 v[24:25], v[24:25], v[240:241] op_sel_hi:[1,0]
	v_pk_mul_f32 v[26:27], v[26:27], v[240:241] op_sel_hi:[1,0]
	v_pk_mul_f32 v[28:29], v[28:29], v[184:185]
	v_pk_mul_f32 v[30:31], v[30:31], v[186:187]
	v_pk_mul_f32 v[24:25], v[24:25], v[188:189]
	v_pk_mul_f32 v[26:27], v[26:27], v[190:191]
	global_store_dwordx4 v[192:193], v[28:31], off offset:512 nt
	global_store_dwordx4 v[192:193], v[24:27], off offset:528 nt
	v_lshl_add_u64 v[192:193], v[192:193], 0, s[12:13]
	v_pk_mul_f32 v[84:85], v[84:85], v[242:243] op_sel_hi:[1,0]
	v_pk_mul_f32 v[86:87], v[86:87], v[242:243] op_sel_hi:[1,0]
	v_pk_mul_f32 v[80:81], v[80:81], v[242:243] op_sel_hi:[1,0]
	v_pk_mul_f32 v[82:83], v[82:83], v[242:243] op_sel_hi:[1,0]
	v_pk_mul_f32 v[84:85], v[84:85], v[132:133]
	v_pk_mul_f32 v[86:87], v[86:87], v[134:135]
	v_pk_mul_f32 v[80:81], v[80:81], v[128:129]
	v_pk_mul_f32 v[82:83], v[82:83], v[130:131]
	global_store_dwordx4 v[192:193], v[84:87], off nt
	global_store_dwordx4 v[192:193], v[80:83], off offset:16 nt
	v_pk_mul_f32 v[20:21], v[20:21], v[242:243] op_sel_hi:[1,0]
	v_pk_mul_f32 v[22:23], v[22:23], v[242:243] op_sel_hi:[1,0]
	v_pk_mul_f32 v[16:17], v[16:17], v[242:243] op_sel_hi:[1,0]
	v_pk_mul_f32 v[18:19], v[18:19], v[242:243] op_sel_hi:[1,0]
	v_pk_mul_f32 v[20:21], v[20:21], v[184:185]
	v_pk_mul_f32 v[22:23], v[22:23], v[186:187]
	v_pk_mul_f32 v[16:17], v[16:17], v[188:189]
	v_pk_mul_f32 v[18:19], v[18:19], v[190:191]
	global_store_dwordx4 v[192:193], v[20:23], off offset:512 nt
	global_store_dwordx4 v[192:193], v[16:19], off offset:528 nt
	v_lshl_add_u64 v[192:193], v[192:193], 0, s[12:13]
	v_pk_mul_f32 v[76:77], v[76:77], v[244:245] op_sel_hi:[1,0]
	v_pk_mul_f32 v[78:79], v[78:79], v[244:245] op_sel_hi:[1,0]
	v_pk_mul_f32 v[72:73], v[72:73], v[244:245] op_sel_hi:[1,0]
	v_pk_mul_f32 v[74:75], v[74:75], v[244:245] op_sel_hi:[1,0]
	v_pk_mul_f32 v[76:77], v[76:77], v[132:133]
	v_pk_mul_f32 v[78:79], v[78:79], v[134:135]
	v_pk_mul_f32 v[72:73], v[72:73], v[128:129]
	v_pk_mul_f32 v[74:75], v[74:75], v[130:131]
	global_store_dwordx4 v[192:193], v[76:79], off nt
	global_store_dwordx4 v[192:193], v[72:75], off offset:16 nt
	v_pk_mul_f32 v[12:13], v[12:13], v[244:245] op_sel_hi:[1,0]
	v_pk_mul_f32 v[14:15], v[14:15], v[244:245] op_sel_hi:[1,0]
	v_pk_mul_f32 v[8:9], v[8:9], v[244:245] op_sel_hi:[1,0]
	v_pk_mul_f32 v[10:11], v[10:11], v[244:245] op_sel_hi:[1,0]
	v_pk_mul_f32 v[12:13], v[12:13], v[184:185]
	v_pk_mul_f32 v[14:15], v[14:15], v[186:187]
	v_pk_mul_f32 v[8:9], v[8:9], v[188:189]
	v_pk_mul_f32 v[10:11], v[10:11], v[190:191]
	global_store_dwordx4 v[192:193], v[12:15], off offset:512 nt
	global_store_dwordx4 v[192:193], v[8:11], off offset:528 nt
	v_lshl_add_u64 v[192:193], v[192:193], 0, s[12:13]
	v_pk_mul_f32 v[68:69], v[68:69], v[246:247] op_sel_hi:[1,0]
	v_pk_mul_f32 v[70:71], v[70:71], v[246:247] op_sel_hi:[1,0]
	v_pk_mul_f32 v[64:65], v[64:65], v[246:247] op_sel_hi:[1,0]
	v_pk_mul_f32 v[66:67], v[66:67], v[246:247] op_sel_hi:[1,0]
	v_pk_mul_f32 v[68:69], v[68:69], v[132:133]
	v_pk_mul_f32 v[70:71], v[70:71], v[134:135]
	v_pk_mul_f32 v[64:65], v[64:65], v[128:129]
	v_pk_mul_f32 v[66:67], v[66:67], v[130:131]
	global_store_dwordx4 v[192:193], v[68:71], off nt
	global_store_dwordx4 v[192:193], v[64:67], off offset:16 nt
	v_pk_mul_f32 v[4:5], v[4:5], v[246:247] op_sel_hi:[1,0]
	v_pk_mul_f32 v[6:7], v[6:7], v[246:247] op_sel_hi:[1,0]
	v_pk_mul_f32 v[0:1], v[0:1], v[246:247] op_sel_hi:[1,0]
	v_pk_mul_f32 v[2:3], v[2:3], v[246:247] op_sel_hi:[1,0]
	v_pk_mul_f32 v[4:5], v[4:5], v[184:185]
	v_pk_mul_f32 v[6:7], v[6:7], v[186:187]
	v_pk_mul_f32 v[0:1], v[0:1], v[188:189]
	v_pk_mul_f32 v[2:3], v[2:3], v[190:191]
	global_store_dwordx4 v[192:193], v[4:7], off offset:512 nt
	global_store_dwordx4 v[192:193], v[0:3], off offset:528 nt
	s_branch .LBB0_1006
.LBB0_1012:
	s_waitcnt vmcnt(0)
	s_lshl_b32 s6, s78, 6
	s_lshl_b32 s18, s58, 6
	s_mov_b32 s14, s22
	s_cmpk_lg_i32 s82, 0x100
	s_cselect_b32 s14, s14, -1
	s_barrier
